# attention steady loop: exposed half of the row-max reduction split into two independent chains merged by one v_max3 (dependency depth 9 to 5)
# speedup vs baseline: 1.0058x; 1.0058x over previous
.LBB0_1277:
	s_lshl_b32 s18, s23, 1
	v_mfma_f32_32x32x16_bf16 v[112:127], v[188:191], v[156:159], v[238:253]
	v_add_u32_e32 v237, s18, v214
	ds_read_b64_tr_b16 v[192:193], v237 offset:24576
	v_add_f32_e32 v128, v80, v81
	v_add_f32_e32 v128, v82, v128
	v_add_f32_e32 v128, v83, v128
	v_add_f32_e32 v128, v84, v128
	v_add_f32_e32 v128, v85, v128
	v_cvt_pk_bf16_f32 v148, v80, v81
	v_cvt_pk_bf16_f32 v149, v82, v83
	ds_read_b64_tr_b16 v[194:195], v237 offset:25088
	s_waitcnt lgkmcnt(8)
	v_mfma_f32_32x32x16_bf16 v[112:127], v[180:183], v[152:155], v[112:127]
	v_add_f32_e32 v80, v86, v128
	v_add_f32_e32 v80, v87, v80
	v_add_f32_e32 v80, v88, v80
	v_add_f32_e32 v82, v89, v80
	v_cvt_pk_bf16_f32 v150, v84, v85
	v_cvt_pk_bf16_f32 v151, v86, v87
	ds_read_b64_tr_b16 v[80:81], v237 offset:28672
	s_waitcnt lgkmcnt(8)
	v_mfma_f32_32x32x16_bf16 v[112:127], v[172:175], v[144:147], v[112:127]
	v_add_f32_e32 v82, v90, v82
	v_add_f32_e32 v82, v91, v82
	v_add_f32_e32 v82, v92, v82
	v_add_f32_e32 v84, v93, v82
	v_cvt_pk_bf16_f32 v140, v88, v89
	v_cvt_pk_bf16_f32 v141, v90, v91
	ds_read_b64_tr_b16 v[82:83], v237 offset:29184
	s_waitcnt lgkmcnt(8)
	v_mfma_f32_32x32x16_bf16 v[112:127], v[164:167], v[136:139], v[112:127]
	v_add_f32_e32 v84, v94, v84
	v_add_f32_e32 v84, v95, v84
	v_add_f32_e32 v84, v64, v84
	v_add_f32_e32 v86, v65, v84
	v_cvt_pk_bf16_f32 v142, v92, v93
	v_cvt_pk_bf16_f32 v143, v94, v95
	ds_read_b64_tr_b16 v[84:85], v237 offset:32768
	s_waitcnt lgkmcnt(8)
	v_mfma_f32_32x32x16_bf16 v[96:111], v[184:187], v[156:159], v[238:253]
	v_add_f32_e32 v86, v66, v86
	v_add_f32_e32 v86, v67, v86
	v_add_f32_e32 v86, v68, v86
	v_add_f32_e32 v88, v69, v86
	v_cvt_pk_bf16_f32 v132, v64, v65
	v_cvt_pk_bf16_f32 v133, v66, v67
	ds_read_b64_tr_b16 v[86:87], v237 offset:33280
	s_waitcnt lgkmcnt(8)
	v_mfma_f32_32x32x16_bf16 v[96:111], v[176:179], v[152:155], v[96:111]
	v_add_f32_e32 v64, v70, v88
	v_add_f32_e32 v64, v71, v64
	v_add_f32_e32 v64, v72, v64
	v_add_f32_e32 v66, v73, v64
	v_cvt_pk_bf16_f32 v134, v68, v69
	v_cvt_pk_bf16_f32 v135, v70, v71
	ds_read_b64_tr_b16 v[64:65], v237 offset:36864
	s_waitcnt lgkmcnt(8)
	v_mfma_f32_32x32x16_bf16 v[96:111], v[168:171], v[144:147], v[96:111]
	v_add_f32_e32 v66, v74, v66
	v_add_f32_e32 v66, v75, v66
	v_add_f32_e32 v66, v76, v66
	v_add_f32_e32 v68, v77, v66
	v_cvt_pk_bf16_f32 v128, v72, v73
	v_cvt_pk_bf16_f32 v129, v74, v75
	v_max_f32_e32 v69, v112, v113
	v_max3_f32 v69, v69, v114, v115
	v_max3_f32 v69, v69, v116, v117
	v_max3_f32 v69, v69, v118, v119
	ds_read_b64_tr_b16 v[66:67], v237 offset:37376
	s_waitcnt lgkmcnt(8)
	v_mfma_f32_32x32x16_bf16 v[96:111], v[160:163], v[136:139], v[96:111]
	v_add_f32_e32 v68, v78, v68
	v_add_f32_e32 v68, v79, v68
	v_add_f32_e32 v236, v236, v68
	v_cvt_pk_bf16_f32 v130, v76, v77
	v_cvt_pk_bf16_f32 v131, v78, v79
	v_max3_f32 v69, v69, v120, v121
	v_max3_f32 v69, v69, v122, v123
	v_max3_f32 v69, v69, v124, v125
	v_max3_f32 v69, v69, v126, v127
	s_add_u32 s30, s98, 0xffffe000
	s_addc_u32 s31, s99, -1
	s_add_i32 s18, s86, s89
	s_nop 0
	s_mov_b32 s23, m0
	s_mov_b32 m0, s18
	s_nop 0
	global_load_lds_dwordx4 v196, s[30:31]
	s_mov_b32 m0, s23
	s_add_u32 s30, s100, 0xffffc000
	s_addc_u32 s31, s101, -1
	s_lshl_b32 s18, s37, 1
	s_add_i32 s18, s18, s90
	s_mov_b32 s23, m0
	s_mov_b32 m0, s18
	s_nop 0
	global_load_lds_dwordx4 v196, s[30:31]
	s_mov_b32 m0, s23
	s_add_u32 s30, s100, 0xffffe000
	s_addc_u32 s31, s101, -1
	s_addk_i32 s18, 0x2000
	s_mov_b32 s23, m0
	s_mov_b32 m0, s18
	s_nop 0
	global_load_lds_dwordx4 v196, s[30:31]
	s_mov_b32 m0, s23
	v_max_f32_e32 v70, v96, v97
	v_max_f32_e32 v71, v104, v105
	v_max3_f32 v70, v70, v98, v99
	v_max3_f32 v71, v71, v106, v107
	v_max3_f32 v70, v70, v100, v101
	v_max3_f32 v71, v71, v108, v109
	v_max3_f32 v70, v70, v102, v103
	v_max3_f32 v71, v71, v110, v111
	v_max3_f32 v68, v69, v70, v71
	v_cmp_lt_f32_e32 vcc, s71, v68
	s_cmp_lg_u64 vcc, 0
	s_cselect_b64 s[50:51], -1, 0
	s_cbranch_vccnz .LBB0_1285

.LBB0_1280:
	s_add_i32 s18, s37, 0x2000
	s_lshl_b32 s23, s86, 1
	v_mfma_f32_32x32x16_bf16 v[80:95], v[192:195], v[156:159], v[238:253]
	v_add_u32_e32 v237, s23, v214
	ds_read_b64_tr_b16 v[180:181], v237 offset:24576
	s_cmpk_lg_i32 s37, 0x4000
	s_cselect_b32 s86, s18, 0
	v_add_f32_e32 v128, v112, v113
	v_add_f32_e32 v128, v114, v128
	v_add_f32_e32 v128, v115, v128
	v_add_f32_e32 v128, v116, v128
	v_add_f32_e32 v128, v117, v128
	v_cvt_pk_bf16_f32 v148, v112, v113
	v_cvt_pk_bf16_f32 v149, v114, v115
	ds_read_b64_tr_b16 v[182:183], v237 offset:25088
	s_waitcnt lgkmcnt(8)
	v_mfma_f32_32x32x16_bf16 v[80:95], v[184:187], v[152:155], v[80:95]
	v_add_f32_e32 v112, v118, v128
	v_add_f32_e32 v112, v119, v112
	v_add_f32_e32 v112, v120, v112
	v_add_f32_e32 v114, v121, v112
	v_cvt_pk_bf16_f32 v150, v116, v117
	v_cvt_pk_bf16_f32 v151, v118, v119
	ds_read_b64_tr_b16 v[112:113], v237 offset:28672
	s_waitcnt lgkmcnt(8)
	v_mfma_f32_32x32x16_bf16 v[80:95], v[172:175], v[144:147], v[80:95]
	v_add_f32_e32 v114, v122, v114
	v_add_f32_e32 v114, v123, v114
	v_add_f32_e32 v114, v124, v114
	v_add_f32_e32 v116, v125, v114
	v_cvt_pk_bf16_f32 v140, v120, v121
	v_cvt_pk_bf16_f32 v141, v122, v123
	ds_read_b64_tr_b16 v[114:115], v237 offset:29184
	s_waitcnt lgkmcnt(8)
	v_mfma_f32_32x32x16_bf16 v[80:95], v[164:167], v[136:139], v[80:95]
	v_add_f32_e32 v116, v126, v116
	v_add_f32_e32 v116, v127, v116
	v_add_f32_e32 v116, v96, v116
	v_add_f32_e32 v118, v97, v116
	v_cvt_pk_bf16_f32 v142, v124, v125
	v_cvt_pk_bf16_f32 v143, v126, v127
	ds_read_b64_tr_b16 v[116:117], v237 offset:32768
	s_waitcnt lgkmcnt(8)
	v_mfma_f32_32x32x16_bf16 v[64:79], v[188:191], v[156:159], v[238:253]
	v_add_f32_e32 v118, v98, v118
	v_add_f32_e32 v118, v99, v118
	v_add_f32_e32 v118, v100, v118
	v_add_f32_e32 v120, v101, v118
	v_cvt_pk_bf16_f32 v132, v96, v97
	v_cvt_pk_bf16_f32 v133, v98, v99
	ds_read_b64_tr_b16 v[118:119], v237 offset:33280
	s_waitcnt lgkmcnt(8)
	v_mfma_f32_32x32x16_bf16 v[64:79], v[176:179], v[152:155], v[64:79]
	v_add_f32_e32 v96, v102, v120
	v_add_f32_e32 v96, v103, v96
	v_add_f32_e32 v96, v104, v96
	v_add_f32_e32 v98, v105, v96
	v_cvt_pk_bf16_f32 v134, v100, v101
	v_cvt_pk_bf16_f32 v135, v102, v103
	ds_read_b64_tr_b16 v[96:97], v237 offset:36864
	s_waitcnt lgkmcnt(8)
	v_mfma_f32_32x32x16_bf16 v[64:79], v[168:171], v[144:147], v[64:79]
	v_add_f32_e32 v98, v106, v98
	v_add_f32_e32 v98, v107, v98
	v_add_f32_e32 v98, v108, v98
	v_add_f32_e32 v100, v109, v98
	v_cvt_pk_bf16_f32 v128, v104, v105
	v_cvt_pk_bf16_f32 v129, v106, v107
	v_max_f32_e32 v101, v80, v81
	v_max3_f32 v101, v101, v82, v83
	v_max3_f32 v101, v101, v84, v85
	v_max3_f32 v101, v101, v86, v87
	ds_read_b64_tr_b16 v[98:99], v237 offset:37376
	s_waitcnt lgkmcnt(8)
	v_mfma_f32_32x32x16_bf16 v[64:79], v[160:163], v[136:139], v[64:79]
	v_add_f32_e32 v100, v110, v100
	v_add_f32_e32 v100, v111, v100
	v_add_f32_e32 v236, v236, v100
	v_cvt_pk_bf16_f32 v130, v108, v109
	v_cvt_pk_bf16_f32 v131, v110, v111
	v_max3_f32 v101, v101, v88, v89
	v_max3_f32 v101, v101, v90, v91
	v_max3_f32 v101, v101, v92, v93
	v_max3_f32 v101, v101, v94, v95
	s_add_i32 s18, s37, s89
	s_mov_b32 s23, m0
	s_mov_b32 m0, s18
	s_nop 0
	global_load_lds_dwordx4 v196, s[98:99]
	s_mov_b32 m0, s23
	s_lshl_b32 s18, s86, 1
	s_add_i32 s18, s18, s90
	s_mov_b32 s23, m0
	s_mov_b32 m0, s18
	s_nop 0
	global_load_lds_dwordx4 v196, s[100:101]
	s_mov_b32 m0, s23
	s_add_u32 s30, s100, 0x2000
	s_addc_u32 s31, s101, 0
	s_addk_i32 s18, 0x2000
	s_mov_b32 s23, m0
	s_mov_b32 m0, s18
	s_nop 0
	global_load_lds_dwordx4 v196, s[30:31]
	s_mov_b32 m0, s23
	v_max_f32_e32 v102, v64, v65
	v_max_f32_e32 v103, v72, v73
	v_max3_f32 v102, v102, v66, v67
	v_max3_f32 v103, v103, v74, v75
	v_max3_f32 v102, v102, v68, v69
	v_max3_f32 v103, v103, v76, v77
	v_max3_f32 v102, v102, v70, v71
	v_max3_f32 v103, v103, v78, v79
	v_max3_f32 v100, v101, v102, v103
	v_cmp_lt_f32_e32 vcc, s71, v100
	s_cmp_lg_u64 vcc, 0
	s_cselect_b64 s[50:51], -1, 0
	s_cbranch_vccnz .LBB0_1288
